# M1: half of each XCD's blocks run attention before the scan (compute-bound and bandwidth-bound halves overlap across the chip)
# baseline (speedup 1.0000x reference)
.LBB0_348:
	v_writelane_b32 v255, s80, 37
	s_nop 1
	v_writelane_b32 v255, s81, 38
	s_or_b64 exec, exec, s[0:1]
	v_readlane_b32 s0, v252, 26
	v_readlane_b32 s1, v252, 27
	v_readlane_b32 s84, v255, 37
	s_andn2_b64 vcc, exec, s[0:1]
	v_readlane_b32 s30, v251, 2
	s_mov_b32 s31, s91
	s_movk_i32 s78, 0xc00
	s_movk_i32 s91, 0x500
	s_movk_i32 s80, 0x600
	s_mov_b32 s81, 0x20000
	s_mov_b32 s92, 0x28000
	s_mov_b32 s93, 0x30000
	s_mov_b32 s96, 0x38000
	s_movk_i32 s97, 0x120
	s_mov_b32 s8, 0x40000
	s_movk_i32 s9, 0x700
	v_readlane_b32 s85, v255, 38
	s_waitcnt lgkmcnt(0)
	s_barrier
	s_cmpk_lg_u32 s88, 0x100
	s_cbranch_scc1 .Lm1_noswap0
	v_readlane_b32 s0, v255, 35
	s_bitcmp1_b32 s0, 3
	s_cbranch_scc1 .LBB0_350
.Lm1_noswap0:
	s_cbranch_vccnz .LBB0_350
.LBB0_349:
	s_ashr_i32 s0, s31, 2
	s_and_b32 s23, s31, 7
	s_and_b32 s0, s0, -8
	s_bfe_u32 s18, s31, 0x10004
	s_or_b32 s2, s0, s23
	s_cmp_eq_u32 s18, 0
	s_mov_b32 s0, 0x9441400
	s_cselect_b32 s3, s0, 0xa541400
	s_movk_i32 s0, 0xd00
	s_cselect_b32 s7, s0, 0x300
	s_movk_i32 s0, 0xe00
	s_cselect_b32 s5, s0, 0x200
	s_movk_i32 s0, 0xf00
	s_cselect_b32 s1, s0, 0x100
	s_mov_b32 s0, 0x68000
	s_cselect_b32 s38, s0, 0x18000
	s_mov_b32 s0, 0x70000
	s_cselect_b32 s10, s0, 0x10000
	s_mov_b32 s0, 0x78000
	s_cselect_b32 s45, 1, 15
	s_cselect_b32 s41, 2, 14
	s_cselect_b32 s37, 3, 13
	s_cselect_b32 s49, 0x400, s78
	s_cselect_b32 s47, s91, 0xb00
	s_cselect_b32 s43, s80, 0xa00
	s_cselect_b32 s39, s9, 0x900
	s_cselect_b32 s48, s81, 0x60000
	s_cselect_b32 s36, 0x900, s9
	s_cselect_b32 s46, s92, 0x58000
	s_cselect_b32 s27, 0xa00, s80
	s_cselect_b32 s44, s93, 0x50000
	s_cselect_b32 s21, 0xb00, s91
	s_cselect_b32 s42, s96, 0x48000
	s_cselect_b32 s11, s78, 0x400
	s_cselect_b32 s40, 0x48000, s96
	s_cselect_b32 s26, 0x50000, s93
	s_cselect_b32 s20, 0x58000, s92
	s_cselect_b32 s4, 0x60000, s81
	s_cselect_b32 s6, s0, 0x8000
	s_cselect_b32 s0, 0x80000, 0
	s_add_u32 s51, s70, s3
	s_addc_u32 s52, s71, 0
	s_ashr_i32 s3, s2, 31
	s_lshl_b64 s[16:17], s[2:3], 7
	s_and_b32 s73, s30, 64
	s_or_b32 s3, s16, s73
	s_mul_i32 s16, s17, 0x1100
	s_mul_hi_u32 s17, s3, 0x1100
	s_add_i32 s74, s17, s16
	s_mul_i32 s75, s3, 0x1100
	s_lshl_b32 s3, s23, 2
	s_lshl_b32 s16, s18, 5
	s_or_b32 s3, s16, s3
	s_mul_hi_i32 s53, s2, 0x44000
	s_mul_i32 s72, s2, 0x44000
	v_mov_b32_e32 v0, s3
	s_mul_hi_i32 s3, s2, 34
	s_mul_i32 s2, s2, 34
	s_or_b32 s2, s2, s18
	v_mov_b32_e32 v71, v213
	s_lshl_b64 s[2:3], s[2:3], 14
	s_add_u32 s2, s68, s2
	v_readfirstlane_b32 s22, v71
	s_addc_u32 s3, s69, s3
	s_lshr_b32 s16, s22, 2
	s_and_b32 s50, s16, 48
	v_and_b32_e32 v75, 15, v71
	s_or_b32 s16, s73, s50
	global_load_dword v68, v0, s[84:85]
	v_or_b32_e32 v0, s16, v75
	v_lshlrev_b32_e32 v2, 7, v0
	v_lshl_add_u64 v[0:1], s[2:3], 0, v[2:3]
	s_ashr_i32 s2, s22, 3
	s_and_b32 s16, s2, 0xffffffe0
	s_ashr_i32 s17, s16, 31
	s_add_u32 s2, s51, s72
	s_addc_u32 s3, s52, s53
	s_add_u32 s22, s76, s75
	v_mov_b32_e32 v14, v71
	s_addc_u32 s23, s77, s74
	s_lshl_b32 s51, s18, 12
	s_add_u32 s52, s2, s51
	v_lshlrev_b32_e32 v2, 4, v14
	s_addc_u32 s53, s3, 0
	v_and_b32_e32 v2, 0xf0, v2
	v_lshl_add_u64 v[8:9], s[52:53], 0, v[2:3]
	s_add_u32 s52, s22, s51
	s_addc_u32 s53, s23, 0
	v_lshl_add_u64 v[10:11], s[52:53], 0, v[2:3]
	v_ashrrev_i32_e32 v2, 4, v14
	v_mad_i64_i32 v[4:5], s[52:53], v2, s89, v[8:9]
	v_mad_i64_i32 v[12:13], s[52:53], v2, s89, v[10:11]
	global_load_dwordx4 v[4:7], v[4:5], off
	s_nop 0
	global_load_dwordx4 v[16:19], v[12:13], off
	v_add_u32_e32 v2, 0x200, v14
	v_ashrrev_i32_e32 v2, 4, v2
	v_mad_i64_i32 v[8:9], s[52:53], v2, s89, v[8:9]
	v_mad_i64_i32 v[10:11], s[52:53], v2, s89, v[10:11]
	global_load_dwordx4 v[20:23], v[8:9], off
	global_load_dwordx4 v[24:27], v[10:11], off
	v_mov_b32_e32 v28, v71
	s_lshl_b32 s51, s45, 8
	s_add_u32 s52, s2, s51
	v_lshlrev_b32_e32 v2, 4, v28
	s_addc_u32 s53, s3, 0
	v_and_b32_e32 v2, 0xf0, v2
	v_lshl_add_u64 v[8:9], s[52:53], 0, v[2:3]
	s_add_u32 s52, s22, s51
	s_addc_u32 s53, s23, 0
	v_lshl_add_u64 v[10:11], s[52:53], 0, v[2:3]
	v_ashrrev_i32_e32 v2, 4, v28
	v_mad_i64_i32 v[12:13], s[52:53], v2, s89, v[8:9]
	v_mad_i64_i32 v[14:15], s[52:53], v2, s89, v[10:11]
	v_add_u32_e32 v2, 0x200, v28
	v_ashrrev_i32_e32 v2, 4, v2
	v_mad_i64_i32 v[8:9], s[52:53], v2, s89, v[8:9]
	v_mad_i64_i32 v[10:11], s[52:53], v2, s89, v[10:11]
	v_mov_b32_e32 v32, v71
	s_lshl_b32 s51, s41, 8
	global_load_dwordx4 v[52:55], v[12:13], off
	global_load_dwordx4 v[78:81], v[14:15], off
	global_load_dwordx4 v[82:85], v[8:9], off
	global_load_dwordx4 v[86:89], v[10:11], off
	s_add_u32 s52, s2, s51
	v_lshlrev_b32_e32 v2, 4, v32
	s_addc_u32 s53, s3, 0
	v_and_b32_e32 v2, 0xf0, v2
	v_lshl_add_u64 v[12:13], s[52:53], 0, v[2:3]
	s_add_u32 s52, s22, s51
	s_addc_u32 s53, s23, 0
	v_lshl_add_u64 v[14:15], s[52:53], 0, v[2:3]
	v_ashrrev_i32_e32 v2, 4, v32
	v_mad_i64_i32 v[8:9], s[52:53], v2, s89, v[12:13]
	v_mad_i64_i32 v[28:29], s[52:53], v2, s89, v[14:15]
	v_add_u32_e32 v2, 0x200, v32
	v_ashrrev_i32_e32 v2, 4, v2
	v_mad_i64_i32 v[12:13], s[52:53], v2, s89, v[12:13]
	v_mad_i64_i32 v[14:15], s[52:53], v2, s89, v[14:15]
	v_mov_b32_e32 v44, v71
	s_lshl_b32 s51, s37, 8
	global_load_dwordx4 v[8:11], v[8:9], off
	s_nop 0
	global_load_dwordx4 v[28:31], v[28:29], off
	s_nop 0
	global_load_dwordx4 v[32:35], v[12:13], off
	global_load_dwordx4 v[56:59], v[14:15], off
	s_add_u32 s52, s2, s51
	v_lshlrev_b32_e32 v2, 4, v44
	s_addc_u32 s53, s3, 0
	v_and_b32_e32 v2, 0xf0, v2
	v_lshl_add_u64 v[40:41], s[52:53], 0, v[2:3]
	s_add_u32 s52, s22, s51
	s_addc_u32 s53, s23, 0
	v_lshl_add_u64 v[42:43], s[52:53], 0, v[2:3]
	v_ashrrev_i32_e32 v2, 4, v44
	v_mad_i64_i32 v[12:13], s[52:53], v2, s89, v[40:41]
	v_mad_i64_i32 v[36:37], s[52:53], v2, s89, v[42:43]
	v_add_u32_e32 v2, 0x200, v44
	v_ashrrev_i32_e32 v2, 4, v2
	v_mad_i64_i32 v[40:41], s[52:53], v2, s89, v[40:41]
	v_mov_b32_e32 v46, v71
	global_load_dwordx4 v[12:15], v[12:13], off
	s_nop 0
	global_load_dwordx4 v[36:39], v[36:37], off
	v_mad_i64_i32 v[44:45], s[52:53], v2, s89, v[42:43]
	global_load_dwordx4 v[40:43], v[40:41], off
	s_nop 0
	global_load_dwordx4 v[60:63], v[44:45], off
	s_barrier
	v_bfe_u32 v74, v71, 4, 2
	v_lshlrev_b32_e32 v2, 4, v46
	v_and_b32_e32 v2, 0xf0, v2
	v_add_u32_e32 v2, 0, v2
	v_lshrrev_b32_e32 v44, 4, v46
	v_mad_u64_u32 v[44:45], s[52:53], v44, s97, v[2:3]
	s_waitcnt vmcnt(15)
	ds_write_b128 v44, v[4:7]
	s_waitcnt vmcnt(14)
	ds_write_b128 v44, v[16:19] offset:18432
	v_add_u32_e32 v4, 0x200, v46
	v_lshrrev_b32_e32 v4, 4, v4
	v_mad_u64_u32 v[4:5], s[52:53], v4, s97, v[2:3]
	v_mov_b32_e32 v2, v71
	s_waitcnt vmcnt(13)
	ds_write_b128 v4, v[20:23]
	s_waitcnt vmcnt(12)
	ds_write_b128 v4, v[24:27] offset:18432
	s_add_u32 s52, s2, s49
	v_lshlrev_b32_e32 v4, 4, v2
	s_addc_u32 s53, s3, 0
	v_and_b32_e32 v4, 0xf0, v4
	v_mov_b32_e32 v5, v3
	v_lshl_add_u64 v[6:7], s[52:53], 0, v[4:5]
	s_add_u32 s52, s22, s49
	v_ashrrev_i32_e32 v18, 4, v2
	v_add_u32_e32 v2, 0x200, v2
	s_addc_u32 s53, s23, 0
	v_ashrrev_i32_e32 v2, 4, v2
	v_lshl_add_u64 v[4:5], s[52:53], 0, v[4:5]
	v_mad_i64_i32 v[16:17], s[52:53], v18, s89, v[6:7]
	v_mad_i64_i32 v[6:7], s[52:53], v2, s89, v[6:7]
	v_mad_i64_i32 v[20:21], s[52:53], v18, s89, v[4:5]
	global_load_dwordx4 v[16:19], v[16:17], off
	s_nop 0
	global_load_dwordx4 v[44:47], v[20:21], off
	v_mad_i64_i32 v[4:5], s[52:53], v2, s89, v[4:5]
	global_load_dwordx4 v[48:51], v[6:7], off
	global_load_dwordx4 v[64:67], v[4:5], off
	v_mul_f32_e32 v2, 0x3fb8aa3b, v68
	v_exp_f32_e32 v2, v2
	v_lshl_add_u64 v[68:69], s[16:17], 1, v[0:1]
	v_lshlrev_b32_e32 v0, 1, v71
	v_mov_b32_e32 v1, v3
	v_mul_f32_e32 v2, 0xc3000000, v2
	v_mul_f32_e32 v2, 0x3fb8aa3b, v2
	v_exp_f32_e32 v70, v2
	v_and_b32_e32 v2, 32, v0
	v_lshrrev_b32_e32 v0, 1, v71
	v_lshl_add_u64 v[4:5], v[68:69], 0, v[2:3]
	v_and_b32_e32 v0, 16, v0
	v_lshl_add_u64 v[72:73], v[4:5], 0, v[0:1]
	v_or_b32_e32 v4, s16, v75
	v_mul_lo_u32 v23, v4, s97
	v_or_b32_e32 v4, s50, v75
	v_mul_u32_u24_e32 v24, 0x120, v4
	v_mov_b32_e32 v4, v3
	v_mov_b32_e32 v6, v3
	s_nop 1
	v_permlane16_swap_b32_e32 v4, v6
	s_lshl_b32 s18, s18, 19
	v_lshlrev_b32_e32 v22, 4, v74
	v_mov_b32_e32 v5, v4
	v_mov_b32_e32 v7, v6
	v_lshl_add_u64 v[20:21], v[72:73], 0, s[18:19]
	s_waitcnt lgkmcnt(0)
	s_barrier
	global_store_dwordx4 v[20:21], v[4:7], off
	v_add3_u32 v76, 0, v24, v22
	v_add3_u32 v75, 0, v23, v22
	ds_read_b128 v[4:7], v76 offset:18432
	ds_read_b128 v[20:23], v76 offset:18496
	ds_read_b128 v[24:27], v75
	ds_read_b128 v[90:93], v75 offset:64
	ds_read_b128 v[94:97], v75 offset:4608
	ds_read_b128 v[98:101], v75 offset:4672
	ds_read_b128 v[102:105], v76 offset:18560
	ds_read_b128 v[106:109], v76 offset:18624
	ds_read_b128 v[110:113], v75 offset:128
	ds_read_b128 v[114:117], v75 offset:192
	ds_read_b128 v[118:121], v75 offset:4736
	ds_read_b128 v[122:125], v75 offset:4800
	v_mul_f32_e32 v126, 0, v70
	v_mov_b32_e32 v127, v126
	v_mov_b32_e32 v128, v126
	v_mov_b32_e32 v129, v126
	s_waitcnt lgkmcnt(9)
	s_nop 0
	v_mfma_f32_16x16x32_bf16 v[24:27], v[24:27], v[4:7], v[126:129]
	s_waitcnt lgkmcnt(7)
	v_mfma_f32_16x16x32_bf16 v[4:7], v[94:97], v[4:7], v[126:129]
	v_mfma_f32_16x16x32_bf16 v[24:27], v[90:93], v[20:23], v[24:27]
	s_waitcnt lgkmcnt(6)
	v_mfma_f32_16x16x32_bf16 v[4:7], v[98:101], v[20:23], v[4:7]
	s_waitcnt lgkmcnt(3)
	v_mfma_f32_16x16x32_bf16 v[20:23], v[110:113], v[102:105], v[24:27]
	s_waitcnt lgkmcnt(1)
	v_mfma_f32_16x16x32_bf16 v[4:7], v[118:121], v[102:105], v[4:7]
	v_mfma_f32_16x16x32_bf16 v[90:93], v[114:117], v[106:109], v[20:23]
	s_waitcnt lgkmcnt(0)
	v_mfma_f32_16x16x32_bf16 v[94:97], v[122:125], v[106:109], v[4:7]
	s_nop 4
	v_mov_b32_e32 v5, v71
	v_mov_b32_e32 v26, v71
	v_lshlrev_b32_e32 v4, 4, v5
	v_and_b32_e32 v4, 0xf0, v4
	v_add_u32_e32 v4, 0, v4
	v_lshrrev_b32_e32 v6, 4, v5
	v_mad_u64_u32 v[6:7], s[16:17], v6, s97, v[4:5]
	v_add_u32_e32 v5, 0x200, v5
	v_lshrrev_b32_e32 v5, 4, v5
	v_mad_u64_u32 v[4:5], s[16:17], v5, s97, v[4:5]
	s_waitcnt vmcnt(16)
	ds_write_b128 v6, v[52:55] offset:36864
	s_waitcnt vmcnt(15)
	ds_write_b128 v6, v[78:81] offset:55296
	s_waitcnt vmcnt(14)
	ds_write_b128 v4, v[82:85] offset:36864
	s_waitcnt vmcnt(13)
	ds_write_b128 v4, v[86:89] offset:55296
	s_add_u32 s16, s2, s47
	v_lshlrev_b32_e32 v4, 4, v26
	s_addc_u32 s17, s3, 0
	v_and_b32_e32 v4, 0xf0, v4
	v_mov_b32_e32 v5, v3
	v_lshl_add_u64 v[24:25], s[16:17], 0, v[4:5]
	s_add_u32 s16, s22, s47
	s_addc_u32 s17, s23, 0
	v_ashrrev_i32_e32 v20, 4, v26
	v_add_u32_e32 v26, 0x200, v26
	v_lshl_add_u64 v[52:53], s[16:17], 0, v[4:5]
	v_ashrrev_i32_e32 v54, 4, v26
	v_mad_i64_i32 v[4:5], s[16:17], v20, s89, v[24:25]
	v_mad_i64_i32 v[20:21], s[16:17], v20, s89, v[52:53]
	v_mad_i64_i32 v[24:25], s[16:17], v54, s89, v[24:25]
	v_mad_i64_i32 v[52:53], s[16:17], v54, s89, v[52:53]
	global_load_dwordx4 v[4:7], v[4:5], off
	v_cvt_pk_bf16_f32 v78, v90, v91
	global_load_dwordx4 v[20:23], v[20:21], off
	v_cvt_pk_bf16_f32 v79, v92, v93
	global_load_dwordx4 v[24:27], v[24:25], off
	v_cvt_pk_bf16_f32 v80, v94, v95
	global_load_dwordx4 v[52:55], v[52:53], off
	v_cvt_pk_bf16_f32 v81, v96, v97
	s_lshl_b32 s18, s45, 15
	v_permlane16_swap_b32_e32 v78, v80
	v_permlane16_swap_b32_e32 v79, v81
	v_lshl_add_u64 v[82:83], v[72:73], 0, s[18:19]
	s_waitcnt lgkmcnt(0)
	s_barrier
	global_store_dwordx4 v[82:83], v[78:81], off
	v_pk_mul_f32 v[84:85], v[70:71], v[96:97] op_sel_hi:[0,1]
	v_pk_mul_f32 v[82:83], v[70:71], v[94:95] op_sel_hi:[0,1]
	v_pk_mul_f32 v[80:81], v[70:71], v[92:93] op_sel_hi:[0,1]
	v_pk_mul_f32 v[78:79], v[70:71], v[90:91] op_sel_hi:[0,1]
	ds_read_b128 v[86:89], v76 offset:55296
	ds_read_b128 v[90:93], v75 offset:36864
	ds_read_b128 v[94:97], v75 offset:41472
	ds_read_b128 v[98:101], v76 offset:55360
	ds_read_b128 v[102:105], v75 offset:36928
	ds_read_b128 v[106:109], v75 offset:41536
	ds_read_b128 v[110:113], v76 offset:55424
	ds_read_b128 v[114:117], v75 offset:36992
	ds_read_b128 v[118:121], v75 offset:41600
	ds_read_b128 v[122:125], v76 offset:55488
	ds_read_b128 v[126:129], v75 offset:37056
	ds_read_b128 v[130:133], v75 offset:41664
	s_waitcnt lgkmcnt(10)
	v_mfma_f32_16x16x32_bf16 v[78:81], v[90:93], v[86:89], v[78:81]
	s_waitcnt lgkmcnt(9)
	v_mfma_f32_16x16x32_bf16 v[82:85], v[94:97], v[86:89], v[82:85]
	s_waitcnt lgkmcnt(7)
	v_mfma_f32_16x16x32_bf16 v[78:81], v[102:105], v[98:101], v[78:81]
	s_waitcnt lgkmcnt(6)
	v_mfma_f32_16x16x32_bf16 v[82:85], v[106:109], v[98:101], v[82:85]
	s_waitcnt lgkmcnt(4)
	v_mfma_f32_16x16x32_bf16 v[78:81], v[114:117], v[110:113], v[78:81]
	s_waitcnt lgkmcnt(3)
	v_mfma_f32_16x16x32_bf16 v[82:85], v[118:121], v[110:113], v[82:85]
	s_waitcnt lgkmcnt(1)
	v_mfma_f32_16x16x32_bf16 v[78:81], v[126:129], v[122:125], v[78:81]
	s_waitcnt lgkmcnt(0)
	v_mfma_f32_16x16x32_bf16 v[82:85], v[130:133], v[122:125], v[82:85]
	v_mov_b32_e32 v77, v71
	s_nop 0
	v_lshlrev_b32_e32 v86, 4, v77
	v_and_b32_e32 v86, 0xf0, v86
	v_add_u32_e32 v86, 0, v86
	v_lshrrev_b32_e32 v87, 4, v77
	v_mad_u64_u32 v[88:89], s[16:17], v87, s97, v[86:87]
	s_waitcnt vmcnt(17)
	ds_write_b128 v88, v[8:11]
	s_waitcnt vmcnt(16)
	ds_write_b128 v88, v[28:31] offset:18432
	v_add_u32_e32 v8, 0x200, v77
	v_lshrrev_b32_e32 v8, 4, v8
	v_mad_u64_u32 v[8:9], s[16:17], v8, s97, v[86:87]
	s_waitcnt vmcnt(15)
	ds_write_b128 v8, v[32:35]
	s_waitcnt vmcnt(14)
	ds_write_b128 v8, v[56:59] offset:18432
	v_mov_b32_e32 v34, v71
	s_add_u32 s16, s2, s43
	v_lshlrev_b32_e32 v8, 4, v34
	s_addc_u32 s17, s3, 0
	v_and_b32_e32 v8, 0xf0, v8
	v_mov_b32_e32 v9, v3
	v_lshl_add_u64 v[32:33], s[16:17], 0, v[8:9]
	s_add_u32 s16, s22, s43
	s_addc_u32 s17, s23, 0
	v_ashrrev_i32_e32 v28, 4, v34
	v_add_u32_e32 v34, 0x200, v34
	v_lshl_add_u64 v[56:57], s[16:17], 0, v[8:9]
	v_ashrrev_i32_e32 v58, 4, v34
	v_mad_i64_i32 v[8:9], s[16:17], v28, s89, v[32:33]
	v_mad_i64_i32 v[28:29], s[16:17], v28, s89, v[56:57]
	v_mad_i64_i32 v[32:33], s[16:17], v58, s89, v[32:33]
	v_mad_i64_i32 v[56:57], s[16:17], v58, s89, v[56:57]
	global_load_dwordx4 v[8:11], v[8:9], off
	v_cvt_pk_bf16_f32 v86, v78, v79
	global_load_dwordx4 v[28:31], v[28:29], off
	v_cvt_pk_bf16_f32 v87, v80, v81
	global_load_dwordx4 v[32:35], v[32:33], off
	v_cvt_pk_bf16_f32 v88, v82, v83
	global_load_dwordx4 v[56:59], v[56:57], off
	v_cvt_pk_bf16_f32 v89, v84, v85
	s_lshl_b32 s18, s41, 15
	v_permlane16_swap_b32_e32 v86, v88
	v_permlane16_swap_b32_e32 v87, v89
	v_lshl_add_u64 v[90:91], v[72:73], 0, s[18:19]
	s_waitcnt lgkmcnt(0)
	s_barrier
	global_store_dwordx4 v[90:91], v[86:89], off
	ds_read_b128 v[86:89], v76 offset:18432
	ds_read_b128 v[90:93], v75
	ds_read_b128 v[94:97], v75 offset:4608
	ds_read_b128 v[98:101], v76 offset:18496
	ds_read_b128 v[102:105], v75 offset:64
	ds_read_b128 v[106:109], v75 offset:4672
	ds_read_b128 v[110:113], v76 offset:18560
	ds_read_b128 v[114:117], v75 offset:128
	ds_read_b128 v[118:121], v75 offset:4736
	ds_read_b128 v[122:125], v76 offset:18624
	ds_read_b128 v[126:129], v75 offset:192
	ds_read_b128 v[130:133], v75 offset:4800
	v_pk_mul_f32 v[80:81], v[70:71], v[80:81] op_sel_hi:[0,1]
	v_pk_mul_f32 v[78:79], v[70:71], v[78:79] op_sel_hi:[0,1]
	v_pk_mul_f32 v[84:85], v[70:71], v[84:85] op_sel_hi:[0,1]
	v_pk_mul_f32 v[82:83], v[70:71], v[82:83] op_sel_hi:[0,1]
	s_waitcnt lgkmcnt(10)
	v_mfma_f32_16x16x32_bf16 v[78:81], v[90:93], v[86:89], v[78:81]
	s_waitcnt lgkmcnt(9)
	v_mfma_f32_16x16x32_bf16 v[82:85], v[94:97], v[86:89], v[82:85]
	s_waitcnt lgkmcnt(7)
	v_mfma_f32_16x16x32_bf16 v[78:81], v[102:105], v[98:101], v[78:81]
	s_waitcnt lgkmcnt(6)
	v_mfma_f32_16x16x32_bf16 v[82:85], v[106:109], v[98:101], v[82:85]
	s_waitcnt lgkmcnt(4)
	v_mfma_f32_16x16x32_bf16 v[78:81], v[114:117], v[110:113], v[78:81]
	s_waitcnt lgkmcnt(3)
	v_mfma_f32_16x16x32_bf16 v[82:85], v[118:121], v[110:113], v[82:85]
	s_waitcnt lgkmcnt(1)
	v_mfma_f32_16x16x32_bf16 v[78:81], v[126:129], v[122:125], v[78:81]
	s_waitcnt lgkmcnt(0)
	v_mfma_f32_16x16x32_bf16 v[82:85], v[130:133], v[122:125], v[82:85]
	v_mov_b32_e32 v77, v71
	s_nop 0
	v_lshlrev_b32_e32 v86, 4, v77
	v_and_b32_e32 v86, 0xf0, v86
	v_add_u32_e32 v86, 0, v86
	v_lshrrev_b32_e32 v87, 4, v77
	v_mad_u64_u32 v[88:89], s[16:17], v87, s97, v[86:87]
	s_waitcnt vmcnt(18)
	ds_write_b128 v88, v[12:15] offset:36864
	s_waitcnt vmcnt(17)
	ds_write_b128 v88, v[36:39] offset:55296
	v_add_u32_e32 v12, 0x200, v77
	v_lshrrev_b32_e32 v12, 4, v12
	v_mad_u64_u32 v[12:13], s[16:17], v12, s97, v[86:87]
	s_waitcnt vmcnt(16)
	ds_write_b128 v12, v[40:43] offset:36864
	s_waitcnt vmcnt(15)
	ds_write_b128 v12, v[60:63] offset:55296
	v_mov_b32_e32 v42, v71
	s_add_u32 s16, s2, s39
	v_lshlrev_b32_e32 v12, 4, v42
	s_addc_u32 s17, s3, 0
	v_and_b32_e32 v12, 0xf0, v12
	v_mov_b32_e32 v13, v3
	v_lshl_add_u64 v[40:41], s[16:17], 0, v[12:13]
	s_add_u32 s16, s22, s39
	s_addc_u32 s17, s23, 0
	v_ashrrev_i32_e32 v36, 4, v42
	v_add_u32_e32 v42, 0x200, v42
	v_lshl_add_u64 v[60:61], s[16:17], 0, v[12:13]
	v_ashrrev_i32_e32 v62, 4, v42
	v_mad_i64_i32 v[12:13], s[16:17], v36, s89, v[40:41]
	v_mad_i64_i32 v[36:37], s[16:17], v36, s89, v[60:61]
	v_mad_i64_i32 v[40:41], s[16:17], v62, s89, v[40:41]
	v_mad_i64_i32 v[60:61], s[16:17], v62, s89, v[60:61]
	global_load_dwordx4 v[12:15], v[12:13], off
	v_cvt_pk_bf16_f32 v86, v78, v79
	global_load_dwordx4 v[36:39], v[36:37], off
	v_cvt_pk_bf16_f32 v87, v80, v81
	global_load_dwordx4 v[40:43], v[40:41], off
	v_cvt_pk_bf16_f32 v88, v82, v83
	global_load_dwordx4 v[60:63], v[60:61], off
	v_cvt_pk_bf16_f32 v89, v84, v85
	s_lshl_b32 s18, s37, 15
	v_permlane16_swap_b32_e32 v86, v88
	v_permlane16_swap_b32_e32 v87, v89
	v_lshl_add_u64 v[90:91], v[72:73], 0, s[18:19]
	s_waitcnt lgkmcnt(0)
	s_barrier
	global_store_dwordx4 v[90:91], v[86:89], off
	ds_read_b128 v[86:89], v76 offset:55296
	ds_read_b128 v[90:93], v75 offset:36864
	ds_read_b128 v[94:97], v75 offset:41472
	ds_read_b128 v[98:101], v76 offset:55360
	ds_read_b128 v[102:105], v75 offset:36928
	ds_read_b128 v[106:109], v75 offset:41536
	ds_read_b128 v[110:113], v76 offset:55424
	ds_read_b128 v[114:117], v75 offset:36992
	ds_read_b128 v[118:121], v75 offset:41600
	ds_read_b128 v[122:125], v76 offset:55488
	ds_read_b128 v[126:129], v75 offset:37056
	ds_read_b128 v[130:133], v75 offset:41664
	v_pk_mul_f32 v[80:81], v[70:71], v[80:81] op_sel_hi:[0,1]
	v_pk_mul_f32 v[78:79], v[70:71], v[78:79] op_sel_hi:[0,1]
	v_pk_mul_f32 v[84:85], v[70:71], v[84:85] op_sel_hi:[0,1]
	v_pk_mul_f32 v[82:83], v[70:71], v[82:83] op_sel_hi:[0,1]
	s_waitcnt lgkmcnt(10)
	v_mfma_f32_16x16x32_bf16 v[78:81], v[90:93], v[86:89], v[78:81]
	s_waitcnt lgkmcnt(9)
	v_mfma_f32_16x16x32_bf16 v[82:85], v[94:97], v[86:89], v[82:85]
	s_waitcnt lgkmcnt(7)
	v_mfma_f32_16x16x32_bf16 v[78:81], v[102:105], v[98:101], v[78:81]
	s_waitcnt lgkmcnt(6)
	v_mfma_f32_16x16x32_bf16 v[82:85], v[106:109], v[98:101], v[82:85]
	s_waitcnt lgkmcnt(4)
	v_mfma_f32_16x16x32_bf16 v[78:81], v[114:117], v[110:113], v[78:81]
	s_waitcnt lgkmcnt(3)
	v_mfma_f32_16x16x32_bf16 v[82:85], v[118:121], v[110:113], v[82:85]
	s_waitcnt lgkmcnt(1)
	v_mfma_f32_16x16x32_bf16 v[78:81], v[126:129], v[122:125], v[78:81]
	s_waitcnt lgkmcnt(0)
	v_mfma_f32_16x16x32_bf16 v[82:85], v[130:133], v[122:125], v[82:85]
	v_mov_b32_e32 v77, v71
	s_mov_b32 s49, s19
	v_lshlrev_b32_e32 v86, 4, v77
	v_and_b32_e32 v86, 0xf0, v86
	v_add_u32_e32 v86, 0, v86
	v_lshrrev_b32_e32 v87, 4, v77
	v_mad_u64_u32 v[88:89], s[16:17], v87, s97, v[86:87]
	s_waitcnt vmcnt(19)
	ds_write_b128 v88, v[16:19]
	s_waitcnt vmcnt(18)
	ds_write_b128 v88, v[44:47] offset:18432
	v_add_u32_e32 v16, 0x200, v77
	v_lshrrev_b32_e32 v16, 4, v16
	v_mad_u64_u32 v[16:17], s[16:17], v16, s97, v[86:87]
	s_waitcnt vmcnt(17)
	ds_write_b128 v16, v[48:51]
	s_waitcnt vmcnt(16)
	ds_write_b128 v16, v[64:67] offset:18432
	v_mov_b32_e32 v50, v71
	v_mov_b32_e32 v17, v3
	v_lshlrev_b32_e32 v16, 4, v50
	v_and_b32_e32 v16, 0xf0, v16
	v_ashrrev_i32_e32 v44, 4, v50
	v_add_u32_e32 v50, 0x200, v50
	v_lshl_add_u64 v[48:49], s[2:3], 0, v[16:17]
	v_lshl_add_u64 v[64:65], s[22:23], 0, v[16:17]
	v_ashrrev_i32_e32 v66, 4, v50
	v_mad_i64_i32 v[16:17], s[16:17], v44, s89, v[48:49]
	v_mad_i64_i32 v[44:45], s[16:17], v44, s89, v[64:65]
	v_mad_i64_i32 v[48:49], s[16:17], v66, s89, v[48:49]
	v_mad_i64_i32 v[64:65], s[16:17], v66, s89, v[64:65]
	global_load_dwordx4 v[16:19], v[16:17], off offset:2048
	v_cvt_pk_bf16_f32 v86, v78, v79
	global_load_dwordx4 v[44:47], v[44:45], off offset:2048
	v_cvt_pk_bf16_f32 v87, v80, v81
	global_load_dwordx4 v[48:51], v[48:49], off offset:2048
	v_cvt_pk_bf16_f32 v88, v82, v83
	global_load_dwordx4 v[64:67], v[64:65], off offset:2048
	v_cvt_pk_bf16_f32 v89, v84, v85
	v_permlane16_swap_b32_e32 v86, v88
	s_nop 0
	v_permlane16_swap_b32_e32 v87, v89
	v_lshl_add_u64 v[90:91], v[72:73], 0, s[48:49]
	s_waitcnt lgkmcnt(0)
	s_barrier
	global_store_dwordx4 v[90:91], v[86:89], off
	ds_read_b128 v[86:89], v76 offset:18432
	ds_read_b128 v[90:93], v75
	ds_read_b128 v[94:97], v75 offset:4608
	ds_read_b128 v[98:101], v76 offset:18496
	ds_read_b128 v[102:105], v75 offset:64
	ds_read_b128 v[106:109], v75 offset:4672
	ds_read_b128 v[110:113], v76 offset:18560
	ds_read_b128 v[114:117], v75 offset:128
	ds_read_b128 v[118:121], v75 offset:4736
	ds_read_b128 v[122:125], v76 offset:18624
	ds_read_b128 v[126:129], v75 offset:192
	ds_read_b128 v[130:133], v75 offset:4800
	v_pk_mul_f32 v[80:81], v[70:71], v[80:81] op_sel_hi:[0,1]
	v_pk_mul_f32 v[78:79], v[70:71], v[78:79] op_sel_hi:[0,1]
	v_pk_mul_f32 v[84:85], v[70:71], v[84:85] op_sel_hi:[0,1]
	v_pk_mul_f32 v[82:83], v[70:71], v[82:83] op_sel_hi:[0,1]
	s_waitcnt lgkmcnt(10)
	v_mfma_f32_16x16x32_bf16 v[78:81], v[90:93], v[86:89], v[78:81]
	s_waitcnt lgkmcnt(9)
	v_mfma_f32_16x16x32_bf16 v[82:85], v[94:97], v[86:89], v[82:85]
	s_waitcnt lgkmcnt(7)
	v_mfma_f32_16x16x32_bf16 v[78:81], v[102:105], v[98:101], v[78:81]
	s_waitcnt lgkmcnt(6)
	v_mfma_f32_16x16x32_bf16 v[82:85], v[106:109], v[98:101], v[82:85]
	s_waitcnt lgkmcnt(4)
	v_mfma_f32_16x16x32_bf16 v[78:81], v[114:117], v[110:113], v[78:81]
	s_waitcnt lgkmcnt(3)
	v_mfma_f32_16x16x32_bf16 v[82:85], v[118:121], v[110:113], v[82:85]
	s_waitcnt lgkmcnt(1)
	v_mfma_f32_16x16x32_bf16 v[78:81], v[126:129], v[122:125], v[78:81]
	s_waitcnt lgkmcnt(0)
	v_mfma_f32_16x16x32_bf16 v[82:85], v[130:133], v[122:125], v[82:85]
	v_mov_b32_e32 v77, v71
	s_mov_b32 s47, s19
	v_lshlrev_b32_e32 v86, 4, v77
	v_and_b32_e32 v86, 0xf0, v86
	v_add_u32_e32 v86, 0, v86
	v_lshrrev_b32_e32 v87, 4, v77
	v_mad_u64_u32 v[88:89], s[16:17], v87, s97, v[86:87]
	s_waitcnt vmcnt(19)
	ds_write_b128 v88, v[4:7] offset:36864
	s_waitcnt vmcnt(18)
	ds_write_b128 v88, v[20:23] offset:55296
	v_add_u32_e32 v4, 0x200, v77
	v_lshrrev_b32_e32 v4, 4, v4
	v_mad_u64_u32 v[4:5], s[16:17], v4, s97, v[86:87]
	s_waitcnt vmcnt(17)
	ds_write_b128 v4, v[24:27] offset:36864
	s_waitcnt vmcnt(16)
	ds_write_b128 v4, v[52:55] offset:55296
	v_mov_b32_e32 v26, v71
	s_add_u32 s16, s2, s36
	v_lshlrev_b32_e32 v4, 4, v26
	s_addc_u32 s17, s3, 0
	v_and_b32_e32 v4, 0xf0, v4
	v_mov_b32_e32 v5, v3
	v_lshl_add_u64 v[24:25], s[16:17], 0, v[4:5]
	s_add_u32 s16, s22, s36
	s_addc_u32 s17, s23, 0
	v_ashrrev_i32_e32 v20, 4, v26
	v_add_u32_e32 v26, 0x200, v26
	v_lshl_add_u64 v[52:53], s[16:17], 0, v[4:5]
	v_ashrrev_i32_e32 v54, 4, v26
	v_mad_i64_i32 v[4:5], s[16:17], v20, s89, v[24:25]
	v_mad_i64_i32 v[20:21], s[16:17], v20, s89, v[52:53]
	v_mad_i64_i32 v[24:25], s[16:17], v54, s89, v[24:25]
	v_mad_i64_i32 v[52:53], s[16:17], v54, s89, v[52:53]
	global_load_dwordx4 v[4:7], v[4:5], off
	v_cvt_pk_bf16_f32 v86, v78, v79
	global_load_dwordx4 v[20:23], v[20:21], off
	v_cvt_pk_bf16_f32 v87, v80, v81
	global_load_dwordx4 v[24:27], v[24:25], off
	v_cvt_pk_bf16_f32 v88, v82, v83
	global_load_dwordx4 v[52:55], v[52:53], off
	v_cvt_pk_bf16_f32 v89, v84, v85
	v_permlane16_swap_b32_e32 v86, v88
	s_nop 0
	v_permlane16_swap_b32_e32 v87, v89
	v_lshl_add_u64 v[90:91], v[72:73], 0, s[46:47]
	s_waitcnt lgkmcnt(0)
	s_barrier
	global_store_dwordx4 v[90:91], v[86:89], off
	ds_read_b128 v[86:89], v76 offset:55296
	ds_read_b128 v[90:93], v75 offset:36864
	ds_read_b128 v[94:97], v75 offset:41472
	ds_read_b128 v[98:101], v76 offset:55360
	ds_read_b128 v[102:105], v75 offset:36928
	ds_read_b128 v[106:109], v75 offset:41536
	ds_read_b128 v[110:113], v76 offset:55424
	ds_read_b128 v[114:117], v75 offset:36992
	ds_read_b128 v[118:121], v75 offset:41600
	ds_read_b128 v[122:125], v76 offset:55488
	ds_read_b128 v[126:129], v75 offset:37056
	ds_read_b128 v[130:133], v75 offset:41664
	v_pk_mul_f32 v[80:81], v[70:71], v[80:81] op_sel_hi:[0,1]
	v_pk_mul_f32 v[78:79], v[70:71], v[78:79] op_sel_hi:[0,1]
	v_pk_mul_f32 v[84:85], v[70:71], v[84:85] op_sel_hi:[0,1]
	v_pk_mul_f32 v[82:83], v[70:71], v[82:83] op_sel_hi:[0,1]
	s_waitcnt lgkmcnt(10)
	v_mfma_f32_16x16x32_bf16 v[78:81], v[90:93], v[86:89], v[78:81]
	s_waitcnt lgkmcnt(9)
	v_mfma_f32_16x16x32_bf16 v[82:85], v[94:97], v[86:89], v[82:85]
	s_waitcnt lgkmcnt(7)
	v_mfma_f32_16x16x32_bf16 v[78:81], v[102:105], v[98:101], v[78:81]
	s_waitcnt lgkmcnt(6)
	v_mfma_f32_16x16x32_bf16 v[82:85], v[106:109], v[98:101], v[82:85]
	s_waitcnt lgkmcnt(4)
	v_mfma_f32_16x16x32_bf16 v[78:81], v[114:117], v[110:113], v[78:81]
	s_waitcnt lgkmcnt(3)
	v_mfma_f32_16x16x32_bf16 v[82:85], v[118:121], v[110:113], v[82:85]
	s_waitcnt lgkmcnt(1)
	v_mfma_f32_16x16x32_bf16 v[78:81], v[126:129], v[122:125], v[78:81]
	s_waitcnt lgkmcnt(0)
	v_mfma_f32_16x16x32_bf16 v[82:85], v[130:133], v[122:125], v[82:85]
	v_mov_b32_e32 v77, v71
	s_mov_b32 s45, s19
	v_lshlrev_b32_e32 v86, 4, v77
	v_and_b32_e32 v86, 0xf0, v86
	v_add_u32_e32 v86, 0, v86
	v_lshrrev_b32_e32 v87, 4, v77
	v_mad_u64_u32 v[88:89], s[16:17], v87, s97, v[86:87]
	s_waitcnt vmcnt(19)
	ds_write_b128 v88, v[8:11]
	s_waitcnt vmcnt(18)
	ds_write_b128 v88, v[28:31] offset:18432
	v_add_u32_e32 v8, 0x200, v77
	v_lshrrev_b32_e32 v8, 4, v8
	v_mad_u64_u32 v[8:9], s[16:17], v8, s97, v[86:87]
	s_waitcnt vmcnt(17)
	ds_write_b128 v8, v[32:35]
	s_waitcnt vmcnt(16)
	ds_write_b128 v8, v[56:59] offset:18432
	v_mov_b32_e32 v34, v71
	s_add_u32 s16, s2, s27
	v_lshlrev_b32_e32 v8, 4, v34
	s_addc_u32 s17, s3, 0
	v_and_b32_e32 v8, 0xf0, v8
	v_mov_b32_e32 v9, v3
	v_lshl_add_u64 v[32:33], s[16:17], 0, v[8:9]
	s_add_u32 s16, s22, s27
	s_addc_u32 s17, s23, 0
	v_ashrrev_i32_e32 v28, 4, v34
	v_add_u32_e32 v34, 0x200, v34
	v_lshl_add_u64 v[56:57], s[16:17], 0, v[8:9]
	v_ashrrev_i32_e32 v58, 4, v34
	v_mad_i64_i32 v[8:9], s[16:17], v28, s89, v[32:33]
	v_mad_i64_i32 v[28:29], s[16:17], v28, s89, v[56:57]
	v_mad_i64_i32 v[32:33], s[16:17], v58, s89, v[32:33]
	v_mad_i64_i32 v[56:57], s[16:17], v58, s89, v[56:57]
	global_load_dwordx4 v[8:11], v[8:9], off
	v_cvt_pk_bf16_f32 v86, v78, v79
	global_load_dwordx4 v[28:31], v[28:29], off
	v_cvt_pk_bf16_f32 v87, v80, v81
	global_load_dwordx4 v[32:35], v[32:33], off
	v_cvt_pk_bf16_f32 v88, v82, v83
	global_load_dwordx4 v[56:59], v[56:57], off
	v_cvt_pk_bf16_f32 v89, v84, v85
	v_permlane16_swap_b32_e32 v86, v88
	s_nop 0
	v_permlane16_swap_b32_e32 v87, v89
	v_lshl_add_u64 v[90:91], v[72:73], 0, s[44:45]
	s_waitcnt lgkmcnt(0)
	s_barrier
	global_store_dwordx4 v[90:91], v[86:89], off
	ds_read_b128 v[86:89], v76 offset:18432
	ds_read_b128 v[90:93], v75
	ds_read_b128 v[94:97], v75 offset:4608
	ds_read_b128 v[98:101], v76 offset:18496
	ds_read_b128 v[102:105], v75 offset:64
	ds_read_b128 v[106:109], v75 offset:4672
	ds_read_b128 v[110:113], v76 offset:18560
	ds_read_b128 v[114:117], v75 offset:128
	ds_read_b128 v[118:121], v75 offset:4736
	ds_read_b128 v[122:125], v76 offset:18624
	ds_read_b128 v[126:129], v75 offset:192
	ds_read_b128 v[130:133], v75 offset:4800
	v_pk_mul_f32 v[80:81], v[70:71], v[80:81] op_sel_hi:[0,1]
	v_pk_mul_f32 v[78:79], v[70:71], v[78:79] op_sel_hi:[0,1]
	v_pk_mul_f32 v[84:85], v[70:71], v[84:85] op_sel_hi:[0,1]
	v_pk_mul_f32 v[82:83], v[70:71], v[82:83] op_sel_hi:[0,1]
	s_waitcnt lgkmcnt(10)
	v_mfma_f32_16x16x32_bf16 v[78:81], v[90:93], v[86:89], v[78:81]
	s_waitcnt lgkmcnt(9)
	v_mfma_f32_16x16x32_bf16 v[82:85], v[94:97], v[86:89], v[82:85]
	s_waitcnt lgkmcnt(7)
	v_mfma_f32_16x16x32_bf16 v[78:81], v[102:105], v[98:101], v[78:81]
	s_waitcnt lgkmcnt(6)
	v_mfma_f32_16x16x32_bf16 v[82:85], v[106:109], v[98:101], v[82:85]
	s_waitcnt lgkmcnt(4)
	v_mfma_f32_16x16x32_bf16 v[78:81], v[114:117], v[110:113], v[78:81]
	s_waitcnt lgkmcnt(3)
	v_mfma_f32_16x16x32_bf16 v[82:85], v[118:121], v[110:113], v[82:85]
	s_waitcnt lgkmcnt(1)
	v_mfma_f32_16x16x32_bf16 v[78:81], v[126:129], v[122:125], v[78:81]
	s_waitcnt lgkmcnt(0)
	v_mfma_f32_16x16x32_bf16 v[82:85], v[130:133], v[122:125], v[82:85]
	v_mov_b32_e32 v77, v71
	s_mov_b32 s43, s19
	v_lshlrev_b32_e32 v86, 4, v77
	v_and_b32_e32 v86, 0xf0, v86
	v_add_u32_e32 v86, 0, v86
	v_lshrrev_b32_e32 v87, 4, v77
	v_mad_u64_u32 v[88:89], s[16:17], v87, s97, v[86:87]
	s_waitcnt vmcnt(19)
	ds_write_b128 v88, v[12:15] offset:36864
	s_waitcnt vmcnt(18)
	ds_write_b128 v88, v[36:39] offset:55296
	v_add_u32_e32 v12, 0x200, v77
	v_lshrrev_b32_e32 v12, 4, v12
	v_mad_u64_u32 v[12:13], s[16:17], v12, s97, v[86:87]
	s_waitcnt vmcnt(17)
	ds_write_b128 v12, v[40:43] offset:36864
	s_waitcnt vmcnt(16)
	ds_write_b128 v12, v[60:63] offset:55296
	v_mov_b32_e32 v42, v71
	s_add_u32 s16, s2, s21
	v_lshlrev_b32_e32 v12, 4, v42
	s_addc_u32 s17, s3, 0
	v_and_b32_e32 v12, 0xf0, v12
	v_mov_b32_e32 v13, v3
	v_lshl_add_u64 v[40:41], s[16:17], 0, v[12:13]
	s_add_u32 s16, s22, s21
	s_addc_u32 s17, s23, 0
	v_ashrrev_i32_e32 v36, 4, v42
	v_add_u32_e32 v42, 0x200, v42
	v_lshl_add_u64 v[60:61], s[16:17], 0, v[12:13]
	v_ashrrev_i32_e32 v62, 4, v42
	v_mad_i64_i32 v[12:13], s[16:17], v36, s89, v[40:41]
	v_mad_i64_i32 v[36:37], s[16:17], v36, s89, v[60:61]
	v_mad_i64_i32 v[40:41], s[16:17], v62, s89, v[40:41]
	v_mad_i64_i32 v[60:61], s[16:17], v62, s89, v[60:61]
	global_load_dwordx4 v[12:15], v[12:13], off
	v_cvt_pk_bf16_f32 v86, v78, v79
	global_load_dwordx4 v[36:39], v[36:37], off
	v_cvt_pk_bf16_f32 v87, v80, v81
	global_load_dwordx4 v[40:43], v[40:41], off
	v_cvt_pk_bf16_f32 v88, v82, v83
	global_load_dwordx4 v[60:63], v[60:61], off
	v_cvt_pk_bf16_f32 v89, v84, v85
	v_permlane16_swap_b32_e32 v86, v88
	s_nop 0
	v_permlane16_swap_b32_e32 v87, v89
	v_lshl_add_u64 v[90:91], v[72:73], 0, s[42:43]
	s_waitcnt lgkmcnt(0)
	s_barrier
	global_store_dwordx4 v[90:91], v[86:89], off
	ds_read_b128 v[86:89], v76 offset:55296
	ds_read_b128 v[90:93], v75 offset:36864
	ds_read_b128 v[94:97], v75 offset:41472
	ds_read_b128 v[98:101], v76 offset:55360
	ds_read_b128 v[102:105], v75 offset:36928
	ds_read_b128 v[106:109], v75 offset:41536
	ds_read_b128 v[110:113], v76 offset:55424
	ds_read_b128 v[114:117], v75 offset:36992
	ds_read_b128 v[118:121], v75 offset:41600
	ds_read_b128 v[122:125], v76 offset:55488
	ds_read_b128 v[126:129], v75 offset:37056
	ds_read_b128 v[130:133], v75 offset:41664
	v_pk_mul_f32 v[80:81], v[70:71], v[80:81] op_sel_hi:[0,1]
	v_pk_mul_f32 v[78:79], v[70:71], v[78:79] op_sel_hi:[0,1]
	v_pk_mul_f32 v[84:85], v[70:71], v[84:85] op_sel_hi:[0,1]
	v_pk_mul_f32 v[82:83], v[70:71], v[82:83] op_sel_hi:[0,1]
	s_waitcnt lgkmcnt(10)
	v_mfma_f32_16x16x32_bf16 v[78:81], v[90:93], v[86:89], v[78:81]
	s_waitcnt lgkmcnt(9)
	v_mfma_f32_16x16x32_bf16 v[82:85], v[94:97], v[86:89], v[82:85]
	s_waitcnt lgkmcnt(7)
	v_mfma_f32_16x16x32_bf16 v[78:81], v[102:105], v[98:101], v[78:81]
	s_waitcnt lgkmcnt(6)
	v_mfma_f32_16x16x32_bf16 v[82:85], v[106:109], v[98:101], v[82:85]
	s_waitcnt lgkmcnt(4)
	v_mfma_f32_16x16x32_bf16 v[78:81], v[114:117], v[110:113], v[78:81]
	s_waitcnt lgkmcnt(3)
	v_mfma_f32_16x16x32_bf16 v[82:85], v[118:121], v[110:113], v[82:85]
	s_waitcnt lgkmcnt(1)
	v_mfma_f32_16x16x32_bf16 v[78:81], v[126:129], v[122:125], v[78:81]
	s_waitcnt lgkmcnt(0)
	v_mfma_f32_16x16x32_bf16 v[82:85], v[130:133], v[122:125], v[82:85]
	v_mov_b32_e32 v77, v71
	v_add_co_u32_e32 v90, vcc, s8, v72
	v_lshlrev_b32_e32 v86, 4, v77
	v_and_b32_e32 v86, 0xf0, v86
	v_add_u32_e32 v86, 0, v86
	v_lshrrev_b32_e32 v87, 4, v77
	v_mad_u64_u32 v[88:89], s[16:17], v87, s97, v[86:87]
	s_waitcnt vmcnt(19)
	ds_write_b128 v88, v[16:19]
	s_waitcnt vmcnt(18)
	ds_write_b128 v88, v[44:47] offset:18432
	v_add_u32_e32 v16, 0x200, v77
	v_lshrrev_b32_e32 v16, 4, v16
	v_mad_u64_u32 v[16:17], s[16:17], v16, s97, v[86:87]
	s_waitcnt vmcnt(17)
	ds_write_b128 v16, v[48:51]
	s_waitcnt vmcnt(16)
	ds_write_b128 v16, v[64:67] offset:18432
	v_mov_b32_e32 v50, v71
	s_add_u32 s16, s2, s11
	v_lshlrev_b32_e32 v16, 4, v50
	s_addc_u32 s17, s3, 0
	v_and_b32_e32 v16, 0xf0, v16
	v_mov_b32_e32 v17, v3
	v_lshl_add_u64 v[48:49], s[16:17], 0, v[16:17]
	s_add_u32 s16, s22, s11
	s_addc_u32 s17, s23, 0
	v_ashrrev_i32_e32 v44, 4, v50
	v_add_u32_e32 v50, 0x200, v50
	v_lshl_add_u64 v[64:65], s[16:17], 0, v[16:17]
	v_ashrrev_i32_e32 v66, 4, v50
	v_mad_i64_i32 v[16:17], s[16:17], v44, s89, v[48:49]
	v_mad_i64_i32 v[44:45], s[16:17], v44, s89, v[64:65]
	v_mad_i64_i32 v[48:49], s[16:17], v66, s89, v[48:49]
	v_mad_i64_i32 v[64:65], s[16:17], v66, s89, v[64:65]
	global_load_dwordx4 v[16:19], v[16:17], off
	v_cvt_pk_bf16_f32 v86, v78, v79
	global_load_dwordx4 v[44:47], v[44:45], off
	v_cvt_pk_bf16_f32 v87, v80, v81
	global_load_dwordx4 v[48:51], v[48:49], off
	v_cvt_pk_bf16_f32 v88, v82, v83
	global_load_dwordx4 v[64:67], v[64:65], off
	v_cvt_pk_bf16_f32 v89, v84, v85
	v_permlane16_swap_b32_e32 v86, v88
	s_nop 0
	v_permlane16_swap_b32_e32 v87, v89
	v_addc_co_u32_e32 v91, vcc, 0, v73, vcc
	s_waitcnt lgkmcnt(0)
	s_barrier
	global_store_dwordx4 v[90:91], v[86:89], off
	ds_read_b128 v[86:89], v76 offset:18432
	ds_read_b128 v[90:93], v75
	ds_read_b128 v[94:97], v75 offset:4608
	ds_read_b128 v[98:101], v76 offset:18496
	ds_read_b128 v[102:105], v75 offset:64
	ds_read_b128 v[106:109], v75 offset:4672
	ds_read_b128 v[110:113], v76 offset:18560
	ds_read_b128 v[114:117], v75 offset:128
	ds_read_b128 v[118:121], v75 offset:4736
	ds_read_b128 v[122:125], v76 offset:18624
	ds_read_b128 v[126:129], v75 offset:192
	ds_read_b128 v[130:133], v75 offset:4800
	v_pk_mul_f32 v[80:81], v[70:71], v[80:81] op_sel_hi:[0,1]
	v_pk_mul_f32 v[78:79], v[70:71], v[78:79] op_sel_hi:[0,1]
	v_pk_mul_f32 v[84:85], v[70:71], v[84:85] op_sel_hi:[0,1]
	v_pk_mul_f32 v[82:83], v[70:71], v[82:83] op_sel_hi:[0,1]
	s_waitcnt lgkmcnt(10)
	v_mfma_f32_16x16x32_bf16 v[78:81], v[90:93], v[86:89], v[78:81]
	s_waitcnt lgkmcnt(9)
	v_mfma_f32_16x16x32_bf16 v[82:85], v[94:97], v[86:89], v[82:85]
	s_waitcnt lgkmcnt(7)
	v_mfma_f32_16x16x32_bf16 v[78:81], v[102:105], v[98:101], v[78:81]
	s_waitcnt lgkmcnt(6)
	v_mfma_f32_16x16x32_bf16 v[82:85], v[106:109], v[98:101], v[82:85]
	s_waitcnt lgkmcnt(4)
	v_mfma_f32_16x16x32_bf16 v[78:81], v[114:117], v[110:113], v[78:81]
	s_waitcnt lgkmcnt(3)
	v_mfma_f32_16x16x32_bf16 v[82:85], v[118:121], v[110:113], v[82:85]
	s_waitcnt lgkmcnt(1)
	v_mfma_f32_16x16x32_bf16 v[78:81], v[126:129], v[122:125], v[78:81]
	s_waitcnt lgkmcnt(0)
	v_mfma_f32_16x16x32_bf16 v[82:85], v[130:133], v[122:125], v[82:85]
	v_mov_b32_e32 v77, v71
	s_mov_b32 s41, s19
	v_lshlrev_b32_e32 v86, 4, v77
	v_and_b32_e32 v86, 0xf0, v86
	v_add_u32_e32 v86, 0, v86
	v_lshrrev_b32_e32 v87, 4, v77
	v_mad_u64_u32 v[88:89], s[16:17], v87, s97, v[86:87]
	s_waitcnt vmcnt(19)
	ds_write_b128 v88, v[4:7] offset:36864
	s_waitcnt vmcnt(18)
	ds_write_b128 v88, v[20:23] offset:55296
	v_add_u32_e32 v4, 0x200, v77
	v_lshrrev_b32_e32 v4, 4, v4
	v_mad_u64_u32 v[4:5], s[16:17], v4, s97, v[86:87]
	s_waitcnt vmcnt(17)
	ds_write_b128 v4, v[24:27] offset:36864
	s_waitcnt vmcnt(16)
	ds_write_b128 v4, v[52:55] offset:55296
	v_mov_b32_e32 v26, v71
	s_add_u32 s16, s2, s7
	v_lshlrev_b32_e32 v4, 4, v26
	s_addc_u32 s17, s3, 0
	v_and_b32_e32 v4, 0xf0, v4
	v_mov_b32_e32 v5, v3
	v_lshl_add_u64 v[24:25], s[16:17], 0, v[4:5]
	s_add_u32 s16, s22, s7
	s_addc_u32 s17, s23, 0
	v_ashrrev_i32_e32 v20, 4, v26
	v_add_u32_e32 v26, 0x200, v26
	v_lshl_add_u64 v[52:53], s[16:17], 0, v[4:5]
	v_ashrrev_i32_e32 v54, 4, v26
	v_mad_i64_i32 v[4:5], s[16:17], v20, s89, v[24:25]
	v_mad_i64_i32 v[20:21], s[16:17], v20, s89, v[52:53]
	v_mad_i64_i32 v[24:25], s[16:17], v54, s89, v[24:25]
	v_mad_i64_i32 v[52:53], s[16:17], v54, s89, v[52:53]
	global_load_dwordx4 v[4:7], v[4:5], off
	v_cvt_pk_bf16_f32 v86, v78, v79
	global_load_dwordx4 v[20:23], v[20:21], off
	v_cvt_pk_bf16_f32 v87, v80, v81
	global_load_dwordx4 v[24:27], v[24:25], off
	v_cvt_pk_bf16_f32 v88, v82, v83
	global_load_dwordx4 v[52:55], v[52:53], off
	v_cvt_pk_bf16_f32 v89, v84, v85
	v_permlane16_swap_b32_e32 v86, v88
	s_nop 0
	v_permlane16_swap_b32_e32 v87, v89
	v_lshl_add_u64 v[90:91], v[72:73], 0, s[40:41]
	s_waitcnt lgkmcnt(0)
	s_barrier
	global_store_dwordx4 v[90:91], v[86:89], off
	ds_read_b128 v[86:89], v76 offset:55296
	ds_read_b128 v[90:93], v75 offset:36864
	ds_read_b128 v[94:97], v75 offset:41472
	ds_read_b128 v[98:101], v76 offset:55360
	ds_read_b128 v[102:105], v75 offset:36928
	ds_read_b128 v[106:109], v75 offset:41536
	ds_read_b128 v[110:113], v76 offset:55424
	ds_read_b128 v[114:117], v75 offset:36992
	ds_read_b128 v[118:121], v75 offset:41600
	ds_read_b128 v[122:125], v76 offset:55488
	ds_read_b128 v[126:129], v75 offset:37056
	ds_read_b128 v[130:133], v75 offset:41664
	v_pk_mul_f32 v[80:81], v[70:71], v[80:81] op_sel_hi:[0,1]
	v_pk_mul_f32 v[78:79], v[70:71], v[78:79] op_sel_hi:[0,1]
	v_pk_mul_f32 v[84:85], v[70:71], v[84:85] op_sel_hi:[0,1]
	v_pk_mul_f32 v[82:83], v[70:71], v[82:83] op_sel_hi:[0,1]
	s_waitcnt lgkmcnt(10)
	v_mfma_f32_16x16x32_bf16 v[78:81], v[90:93], v[86:89], v[78:81]
	s_waitcnt lgkmcnt(9)
	v_mfma_f32_16x16x32_bf16 v[82:85], v[94:97], v[86:89], v[82:85]
	s_waitcnt lgkmcnt(7)
	v_mfma_f32_16x16x32_bf16 v[78:81], v[102:105], v[98:101], v[78:81]
	s_waitcnt lgkmcnt(6)
	v_mfma_f32_16x16x32_bf16 v[82:85], v[106:109], v[98:101], v[82:85]
	s_waitcnt lgkmcnt(4)
	v_mfma_f32_16x16x32_bf16 v[78:81], v[114:117], v[110:113], v[78:81]
	s_waitcnt lgkmcnt(3)
	v_mfma_f32_16x16x32_bf16 v[82:85], v[118:121], v[110:113], v[82:85]
	s_waitcnt lgkmcnt(1)
	v_mfma_f32_16x16x32_bf16 v[78:81], v[126:129], v[122:125], v[78:81]
	s_waitcnt lgkmcnt(0)
	v_mfma_f32_16x16x32_bf16 v[82:85], v[130:133], v[122:125], v[82:85]
	v_mov_b32_e32 v77, v71
	s_mov_b32 s27, s19
	v_lshlrev_b32_e32 v86, 4, v77
	v_and_b32_e32 v86, 0xf0, v86
	v_add_u32_e32 v86, 0, v86
	v_lshrrev_b32_e32 v87, 4, v77
	v_mad_u64_u32 v[88:89], s[16:17], v87, s97, v[86:87]
	s_waitcnt vmcnt(19)
	ds_write_b128 v88, v[8:11]
	s_waitcnt vmcnt(18)
	ds_write_b128 v88, v[28:31] offset:18432
	v_add_u32_e32 v8, 0x200, v77
	v_lshrrev_b32_e32 v8, 4, v8
	v_mad_u64_u32 v[8:9], s[16:17], v8, s97, v[86:87]
	s_waitcnt vmcnt(17)
	ds_write_b128 v8, v[32:35]
	s_waitcnt vmcnt(16)
	ds_write_b128 v8, v[56:59] offset:18432
	v_mov_b32_e32 v34, v71
	s_add_u32 s16, s2, s5
	v_lshlrev_b32_e32 v8, 4, v34
	s_addc_u32 s17, s3, 0
	v_and_b32_e32 v8, 0xf0, v8
	v_mov_b32_e32 v9, v3
	v_lshl_add_u64 v[32:33], s[16:17], 0, v[8:9]
	s_add_u32 s16, s22, s5
	s_addc_u32 s17, s23, 0
	v_ashrrev_i32_e32 v28, 4, v34
	v_add_u32_e32 v34, 0x200, v34
	v_lshl_add_u64 v[56:57], s[16:17], 0, v[8:9]
	v_ashrrev_i32_e32 v58, 4, v34
	v_mad_i64_i32 v[8:9], s[16:17], v28, s89, v[32:33]
	v_mad_i64_i32 v[28:29], s[16:17], v28, s89, v[56:57]
	v_mad_i64_i32 v[32:33], s[16:17], v58, s89, v[32:33]
	v_mad_i64_i32 v[56:57], s[16:17], v58, s89, v[56:57]
	global_load_dwordx4 v[8:11], v[8:9], off
	v_cvt_pk_bf16_f32 v86, v78, v79
	global_load_dwordx4 v[28:31], v[28:29], off
	v_cvt_pk_bf16_f32 v87, v80, v81
	global_load_dwordx4 v[32:35], v[32:33], off
	v_cvt_pk_bf16_f32 v88, v82, v83
	global_load_dwordx4 v[56:59], v[56:57], off
	v_cvt_pk_bf16_f32 v89, v84, v85
	v_permlane16_swap_b32_e32 v86, v88
	s_nop 0
	v_permlane16_swap_b32_e32 v87, v89
	v_lshl_add_u64 v[90:91], v[72:73], 0, s[26:27]
	s_waitcnt lgkmcnt(0)
	s_barrier
	global_store_dwordx4 v[90:91], v[86:89], off
	ds_read_b128 v[86:89], v76 offset:18432
	ds_read_b128 v[90:93], v75
	ds_read_b128 v[94:97], v75 offset:4608
	ds_read_b128 v[98:101], v76 offset:18496
	ds_read_b128 v[102:105], v75 offset:64
	ds_read_b128 v[106:109], v75 offset:4672
	ds_read_b128 v[110:113], v76 offset:18560
	ds_read_b128 v[114:117], v75 offset:128
	ds_read_b128 v[118:121], v75 offset:4736
	ds_read_b128 v[122:125], v76 offset:18624
	ds_read_b128 v[126:129], v75 offset:192
	ds_read_b128 v[130:133], v75 offset:4800
	v_pk_mul_f32 v[80:81], v[70:71], v[80:81] op_sel_hi:[0,1]
	v_pk_mul_f32 v[78:79], v[70:71], v[78:79] op_sel_hi:[0,1]
	v_pk_mul_f32 v[84:85], v[70:71], v[84:85] op_sel_hi:[0,1]
	v_pk_mul_f32 v[82:83], v[70:71], v[82:83] op_sel_hi:[0,1]
	s_waitcnt lgkmcnt(10)
	v_mfma_f32_16x16x32_bf16 v[78:81], v[90:93], v[86:89], v[78:81]
	s_waitcnt lgkmcnt(9)
	v_mfma_f32_16x16x32_bf16 v[82:85], v[94:97], v[86:89], v[82:85]
	s_waitcnt lgkmcnt(7)
	v_mfma_f32_16x16x32_bf16 v[78:81], v[102:105], v[98:101], v[78:81]
	s_waitcnt lgkmcnt(6)
	v_mfma_f32_16x16x32_bf16 v[82:85], v[106:109], v[98:101], v[82:85]
	s_waitcnt lgkmcnt(4)
	v_mfma_f32_16x16x32_bf16 v[78:81], v[114:117], v[110:113], v[78:81]
	s_waitcnt lgkmcnt(3)
	v_mfma_f32_16x16x32_bf16 v[82:85], v[118:121], v[110:113], v[82:85]
	s_waitcnt lgkmcnt(1)
	v_mfma_f32_16x16x32_bf16 v[78:81], v[126:129], v[122:125], v[78:81]
	s_waitcnt lgkmcnt(0)
	v_mfma_f32_16x16x32_bf16 v[82:85], v[130:133], v[122:125], v[82:85]
	v_mov_b32_e32 v77, v71
	s_add_u32 s2, s2, s1
	v_lshlrev_b32_e32 v86, 4, v77
	v_and_b32_e32 v86, 0xf0, v86
	v_add_u32_e32 v86, 0, v86
	v_lshrrev_b32_e32 v87, 4, v77
	v_mad_u64_u32 v[88:89], s[16:17], v87, s97, v[86:87]
	s_waitcnt vmcnt(19)
	ds_write_b128 v88, v[12:15] offset:36864
	s_waitcnt vmcnt(18)
	ds_write_b128 v88, v[36:39] offset:55296
	v_add_u32_e32 v12, 0x200, v77
	v_lshrrev_b32_e32 v12, 4, v12
	v_mad_u64_u32 v[12:13], s[16:17], v12, s97, v[86:87]
	s_waitcnt vmcnt(17)
	ds_write_b128 v12, v[40:43] offset:36864
	s_waitcnt vmcnt(16)
	ds_write_b128 v12, v[60:63] offset:55296
	v_mov_b32_e32 v42, v71
	s_addc_u32 s3, s3, 0
	v_lshlrev_b32_e32 v12, 4, v42
	v_and_b32_e32 v12, 0xf0, v12
	v_mov_b32_e32 v13, v3
	v_lshl_add_u64 v[40:41], s[2:3], 0, v[12:13]
	s_add_u32 s2, s22, s1
	s_addc_u32 s3, s23, 0
	v_ashrrev_i32_e32 v36, 4, v42
	v_add_u32_e32 v42, 0x200, v42
	v_lshl_add_u64 v[60:61], s[2:3], 0, v[12:13]
	v_ashrrev_i32_e32 v62, 4, v42
	v_mad_i64_i32 v[12:13], s[2:3], v36, s89, v[40:41]
	v_mad_i64_i32 v[36:37], s[2:3], v36, s89, v[60:61]
	v_mad_i64_i32 v[40:41], s[2:3], v62, s89, v[40:41]
	v_mad_i64_i32 v[60:61], s[2:3], v62, s89, v[60:61]
	global_load_dwordx4 v[12:15], v[12:13], off
	s_mov_b32 s21, s19
	global_load_dwordx4 v[36:39], v[36:37], off
	v_cvt_pk_bf16_f32 v86, v78, v79
	global_load_dwordx4 v[40:43], v[40:41], off
	v_cvt_pk_bf16_f32 v87, v80, v81
	global_load_dwordx4 v[60:63], v[60:61], off
	v_cvt_pk_bf16_f32 v88, v82, v83
	v_cvt_pk_bf16_f32 v89, v84, v85
	s_nop 0
	v_permlane16_swap_b32_e32 v86, v88
	v_permlane16_swap_b32_e32 v87, v89
	v_lshl_add_u64 v[90:91], v[72:73], 0, s[20:21]
	s_waitcnt lgkmcnt(0)
	s_barrier
	global_store_dwordx4 v[90:91], v[86:89], off
	ds_read_b128 v[86:89], v76 offset:55296
	ds_read_b128 v[90:93], v75 offset:36864
	ds_read_b128 v[94:97], v75 offset:41472
	ds_read_b128 v[98:101], v76 offset:55360
	ds_read_b128 v[102:105], v75 offset:36928
	ds_read_b128 v[106:109], v75 offset:41536
	ds_read_b128 v[110:113], v76 offset:55424
	ds_read_b128 v[114:117], v75 offset:36992
	ds_read_b128 v[118:121], v75 offset:41600
	ds_read_b128 v[122:125], v76 offset:55488
	ds_read_b128 v[126:129], v75 offset:37056
	ds_read_b128 v[130:133], v75 offset:41664
	v_pk_mul_f32 v[80:81], v[70:71], v[80:81] op_sel_hi:[0,1]
	v_pk_mul_f32 v[78:79], v[70:71], v[78:79] op_sel_hi:[0,1]
	v_pk_mul_f32 v[84:85], v[70:71], v[84:85] op_sel_hi:[0,1]
	v_pk_mul_f32 v[82:83], v[70:71], v[82:83] op_sel_hi:[0,1]
	s_waitcnt lgkmcnt(10)
	v_mfma_f32_16x16x32_bf16 v[78:81], v[90:93], v[86:89], v[78:81]
	s_waitcnt lgkmcnt(9)
	v_mfma_f32_16x16x32_bf16 v[82:85], v[94:97], v[86:89], v[82:85]
	s_waitcnt lgkmcnt(7)
	v_mfma_f32_16x16x32_bf16 v[78:81], v[102:105], v[98:101], v[78:81]
	s_waitcnt lgkmcnt(6)
	v_mfma_f32_16x16x32_bf16 v[82:85], v[106:109], v[98:101], v[82:85]
	s_waitcnt lgkmcnt(4)
	v_mfma_f32_16x16x32_bf16 v[78:81], v[114:117], v[110:113], v[78:81]
	s_waitcnt lgkmcnt(3)
	v_mfma_f32_16x16x32_bf16 v[82:85], v[118:121], v[110:113], v[82:85]
	s_waitcnt lgkmcnt(1)
	v_mfma_f32_16x16x32_bf16 v[78:81], v[126:129], v[122:125], v[78:81]
	s_waitcnt lgkmcnt(0)
	v_mfma_f32_16x16x32_bf16 v[82:85], v[130:133], v[122:125], v[82:85]
	v_mov_b32_e32 v77, v71
	s_mov_b32 s5, s19
	v_lshlrev_b32_e32 v86, 4, v77
	v_and_b32_e32 v86, 0xf0, v86
	v_add_u32_e32 v86, 0, v86
	v_lshrrev_b32_e32 v87, 4, v77
	v_mad_u64_u32 v[88:89], s[2:3], v87, s97, v[86:87]
	s_waitcnt vmcnt(19)
	ds_write_b128 v88, v[16:19]
	s_waitcnt vmcnt(18)
	ds_write_b128 v88, v[44:47] offset:18432
	v_add_u32_e32 v16, 0x200, v77
	v_lshrrev_b32_e32 v16, 4, v16
	v_mad_u64_u32 v[16:17], s[2:3], v16, s97, v[86:87]
	s_waitcnt vmcnt(17)
	ds_write_b128 v16, v[48:51]
	s_waitcnt vmcnt(16)
	ds_write_b128 v16, v[64:67] offset:18432
	v_cvt_pk_bf16_f32 v16, v78, v79
	v_cvt_pk_bf16_f32 v17, v80, v81
	v_cvt_pk_bf16_f32 v18, v82, v83
	v_cvt_pk_bf16_f32 v19, v84, v85
	s_nop 0
	v_permlane16_swap_b32_e32 v16, v18
	v_permlane16_swap_b32_e32 v17, v19
	v_lshl_add_u64 v[44:45], v[72:73], 0, s[4:5]
	s_waitcnt lgkmcnt(0)
	s_barrier
	global_store_dwordx4 v[44:45], v[16:19], off
	v_pk_mul_f32 v[46:47], v[70:71], v[84:85] op_sel_hi:[0,1]
	v_pk_mul_f32 v[44:45], v[70:71], v[82:83] op_sel_hi:[0,1]
	v_pk_mul_f32 v[18:19], v[70:71], v[80:81] op_sel_hi:[0,1]
	v_pk_mul_f32 v[16:17], v[70:71], v[78:79] op_sel_hi:[0,1]
	ds_read_b128 v[48:51], v76 offset:18432
	ds_read_b128 v[64:67], v75
	ds_read_b128 v[78:81], v75 offset:4608
	ds_read_b128 v[82:85], v76 offset:18496
	ds_read_b128 v[86:89], v75 offset:64
	ds_read_b128 v[90:93], v75 offset:4672
	ds_read_b128 v[94:97], v76 offset:18560
	ds_read_b128 v[98:101], v75 offset:128
	ds_read_b128 v[102:105], v75 offset:4736
	ds_read_b128 v[106:109], v76 offset:18624
	ds_read_b128 v[110:113], v75 offset:192
	ds_read_b128 v[114:117], v75 offset:4800
	s_waitcnt lgkmcnt(10)
	v_mfma_f32_16x16x32_bf16 v[16:19], v[64:67], v[48:51], v[16:19]
	s_waitcnt lgkmcnt(9)
	v_mfma_f32_16x16x32_bf16 v[44:47], v[78:81], v[48:51], v[44:47]
	s_waitcnt lgkmcnt(7)
	v_mfma_f32_16x16x32_bf16 v[16:19], v[86:89], v[82:85], v[16:19]
	s_waitcnt lgkmcnt(6)
	v_mfma_f32_16x16x32_bf16 v[44:47], v[90:93], v[82:85], v[44:47]
	s_waitcnt lgkmcnt(4)
	v_mfma_f32_16x16x32_bf16 v[16:19], v[98:101], v[94:97], v[16:19]
	s_waitcnt lgkmcnt(3)
	v_mfma_f32_16x16x32_bf16 v[44:47], v[102:105], v[94:97], v[44:47]
	s_waitcnt lgkmcnt(1)
	v_mfma_f32_16x16x32_bf16 v[16:19], v[110:113], v[106:109], v[16:19]
	s_waitcnt lgkmcnt(0)
	v_mfma_f32_16x16x32_bf16 v[44:47], v[114:117], v[106:109], v[44:47]
	v_mov_b32_e32 v49, v71
	s_mov_b32 s39, s19
	v_lshlrev_b32_e32 v48, 4, v49
	v_and_b32_e32 v48, 0xf0, v48
	v_add_u32_e32 v48, 0, v48
	v_lshrrev_b32_e32 v50, 4, v49
	v_mad_u64_u32 v[50:51], s[2:3], v50, s97, v[48:49]
	s_waitcnt vmcnt(15)
	ds_write_b128 v50, v[4:7] offset:36864
	s_waitcnt vmcnt(14)
	ds_write_b128 v50, v[20:23] offset:55296
	v_add_u32_e32 v4, 0x200, v49
	v_lshrrev_b32_e32 v4, 4, v4
	v_mad_u64_u32 v[4:5], s[2:3], v4, s97, v[48:49]
	s_waitcnt vmcnt(13)
	ds_write_b128 v4, v[24:27] offset:36864
	s_waitcnt vmcnt(12)
	ds_write_b128 v4, v[52:55] offset:55296
	v_cvt_pk_bf16_f32 v4, v16, v17
	v_cvt_pk_bf16_f32 v5, v18, v19
	v_cvt_pk_bf16_f32 v6, v44, v45
	v_cvt_pk_bf16_f32 v7, v46, v47
	s_nop 0
	v_permlane16_swap_b32_e32 v4, v6
	v_permlane16_swap_b32_e32 v5, v7
	v_lshl_add_u64 v[20:21], v[72:73], 0, s[38:39]
	s_waitcnt lgkmcnt(0)
	s_barrier
	global_store_dwordx4 v[20:21], v[4:7], off
	s_nop 1
	v_pk_mul_f32 v[6:7], v[70:71], v[18:19] op_sel_hi:[0,1]
	v_pk_mul_f32 v[4:5], v[70:71], v[16:17] op_sel_hi:[0,1]
	v_pk_mul_f32 v[18:19], v[70:71], v[46:47] op_sel_hi:[0,1]
	v_pk_mul_f32 v[16:17], v[70:71], v[44:45] op_sel_hi:[0,1]
	ds_read_b128 v[20:23], v76 offset:55296
	ds_read_b128 v[24:27], v75 offset:36864
	ds_read_b128 v[44:47], v75 offset:41472
	ds_read_b128 v[48:51], v76 offset:55360
	ds_read_b128 v[52:55], v75 offset:36928
	ds_read_b128 v[64:67], v75 offset:41536
	ds_read_b128 v[78:81], v76 offset:55424
	ds_read_b128 v[82:85], v75 offset:36992
	ds_read_b128 v[86:89], v75 offset:41600
	ds_read_b128 v[90:93], v76 offset:55488
	ds_read_b128 v[94:97], v75 offset:37056
	ds_read_b128 v[98:101], v75 offset:41664
	s_waitcnt lgkmcnt(10)
	v_mfma_f32_16x16x32_bf16 v[4:7], v[24:27], v[20:23], v[4:7]
	s_waitcnt lgkmcnt(9)
	v_mfma_f32_16x16x32_bf16 v[16:19], v[44:47], v[20:23], v[16:19]
	s_waitcnt lgkmcnt(7)
	v_mfma_f32_16x16x32_bf16 v[4:7], v[52:55], v[48:51], v[4:7]
	s_waitcnt lgkmcnt(6)
	v_mfma_f32_16x16x32_bf16 v[16:19], v[64:67], v[48:51], v[16:19]
	s_waitcnt lgkmcnt(4)
	v_mfma_f32_16x16x32_bf16 v[4:7], v[82:85], v[78:81], v[4:7]
	s_waitcnt lgkmcnt(3)
	v_mfma_f32_16x16x32_bf16 v[16:19], v[86:89], v[78:81], v[16:19]
	s_waitcnt lgkmcnt(1)
	v_mfma_f32_16x16x32_bf16 v[4:7], v[94:97], v[90:93], v[4:7]
	s_waitcnt lgkmcnt(0)
	v_mfma_f32_16x16x32_bf16 v[16:19], v[98:101], v[90:93], v[16:19]
	v_mov_b32_e32 v21, v71
	s_mov_b32 s11, s19
	v_lshlrev_b32_e32 v20, 4, v21
	v_and_b32_e32 v20, 0xf0, v20
	v_add_u32_e32 v20, 0, v20
	v_lshrrev_b32_e32 v22, 4, v21
	v_mad_u64_u32 v[22:23], s[2:3], v22, s97, v[20:21]
	s_waitcnt vmcnt(11)
	ds_write_b128 v22, v[8:11]
	s_waitcnt vmcnt(10)
	ds_write_b128 v22, v[28:31] offset:18432
	v_add_u32_e32 v8, 0x200, v21
	v_lshrrev_b32_e32 v8, 4, v8
	v_mad_u64_u32 v[8:9], s[2:3], v8, s97, v[20:21]
	s_waitcnt vmcnt(9)
	ds_write_b128 v8, v[32:35]
	s_waitcnt vmcnt(8)
	ds_write_b128 v8, v[56:59] offset:18432
	v_cvt_pk_bf16_f32 v8, v4, v5
	v_cvt_pk_bf16_f32 v9, v6, v7
	v_cvt_pk_bf16_f32 v10, v16, v17
	v_cvt_pk_bf16_f32 v11, v18, v19
	s_nop 0
	v_permlane16_swap_b32_e32 v8, v10
	v_permlane16_swap_b32_e32 v9, v11
	v_lshl_add_u64 v[20:21], v[72:73], 0, s[10:11]
	s_waitcnt lgkmcnt(0)
	s_barrier
	global_store_dwordx4 v[20:21], v[8:11], off
	v_pk_mul_f32 v[6:7], v[70:71], v[6:7] op_sel_hi:[0,1]
	v_pk_mul_f32 v[4:5], v[70:71], v[4:5] op_sel_hi:[0,1]
	v_pk_mul_f32 v[10:11], v[70:71], v[18:19] op_sel_hi:[0,1]
	v_pk_mul_f32 v[8:9], v[70:71], v[16:17] op_sel_hi:[0,1]
	ds_read_b128 v[16:19], v76 offset:18432
	ds_read_b128 v[20:23], v75
	ds_read_b128 v[24:27], v75 offset:4608
	ds_read_b128 v[28:31], v76 offset:18496
	ds_read_b128 v[32:35], v75 offset:64
	ds_read_b128 v[44:47], v75 offset:4672
	ds_read_b128 v[48:51], v76 offset:18560
	ds_read_b128 v[52:55], v75 offset:128
	ds_read_b128 v[56:59], v75 offset:4736
	ds_read_b128 v[64:67], v76 offset:18624
	ds_read_b128 v[78:81], v75 offset:192
	ds_read_b128 v[82:85], v75 offset:4800
	s_waitcnt lgkmcnt(10)
	v_mfma_f32_16x16x32_bf16 v[4:7], v[20:23], v[16:19], v[4:7]
	s_waitcnt lgkmcnt(9)
	v_mfma_f32_16x16x32_bf16 v[8:11], v[24:27], v[16:19], v[8:11]
	s_waitcnt lgkmcnt(7)
	v_mfma_f32_16x16x32_bf16 v[4:7], v[32:35], v[28:31], v[4:7]
	s_waitcnt lgkmcnt(6)
	v_mfma_f32_16x16x32_bf16 v[8:11], v[44:47], v[28:31], v[8:11]
	s_waitcnt lgkmcnt(4)
	v_mfma_f32_16x16x32_bf16 v[4:7], v[52:55], v[48:51], v[4:7]
	s_waitcnt lgkmcnt(3)
	v_mfma_f32_16x16x32_bf16 v[8:11], v[56:59], v[48:51], v[8:11]
	s_waitcnt lgkmcnt(1)
	v_mfma_f32_16x16x32_bf16 v[4:7], v[78:81], v[64:67], v[4:7]
	s_waitcnt lgkmcnt(0)
	v_mfma_f32_16x16x32_bf16 v[8:11], v[82:85], v[64:67], v[8:11]
	s_mov_b32 s7, s19
	v_lshlrev_b32_e32 v16, 4, v71
	v_and_b32_e32 v16, 0xf0, v16
	v_add_u32_e32 v16, 0, v16
	v_lshrrev_b32_e32 v17, 4, v71
	v_mad_u64_u32 v[18:19], s[2:3], v17, s97, v[16:17]
	s_waitcnt vmcnt(7)
	ds_write_b128 v18, v[12:15] offset:36864
	s_waitcnt vmcnt(6)
	ds_write_b128 v18, v[36:39] offset:55296
	v_add_u32_e32 v12, 0x200, v71
	v_lshrrev_b32_e32 v12, 4, v12
	v_mad_u64_u32 v[12:13], s[2:3], v12, s97, v[16:17]
	s_waitcnt vmcnt(5)
	ds_write_b128 v12, v[40:43] offset:36864
	s_waitcnt vmcnt(4)
	ds_write_b128 v12, v[60:63] offset:55296
	v_cvt_pk_bf16_f32 v12, v4, v5
	v_cvt_pk_bf16_f32 v13, v6, v7
	v_cvt_pk_bf16_f32 v14, v8, v9
	v_cvt_pk_bf16_f32 v15, v10, v11
	s_nop 0
	v_permlane16_swap_b32_e32 v12, v14
	v_permlane16_swap_b32_e32 v13, v15
	v_lshl_add_u64 v[16:17], v[72:73], 0, s[6:7]
	s_waitcnt lgkmcnt(0)
	s_barrier
	global_store_dwordx4 v[16:17], v[12:15], off
	ds_read_b128 v[12:15], v76 offset:55296
	ds_read_b128 v[16:19], v75 offset:36864
	ds_read_b128 v[20:23], v75 offset:41472
	ds_read_b128 v[24:27], v76 offset:55360
	ds_read_b128 v[28:31], v75 offset:36928
	ds_read_b128 v[32:35], v75 offset:41536
	ds_read_b128 v[36:39], v76 offset:55424
	ds_read_b128 v[40:43], v75 offset:36992
	ds_read_b128 v[44:47], v75 offset:41600
	ds_read_b128 v[48:51], v76 offset:55488
	ds_read_b128 v[52:55], v75 offset:37056
	ds_read_b128 v[56:59], v75 offset:41664
	v_pk_mul_f32 v[6:7], v[70:71], v[6:7] op_sel_hi:[0,1]
	v_pk_mul_f32 v[4:5], v[70:71], v[4:5] op_sel_hi:[0,1]
	v_pk_mul_f32 v[10:11], v[70:71], v[10:11] op_sel_hi:[0,1]
	v_pk_mul_f32 v[8:9], v[70:71], v[8:9] op_sel_hi:[0,1]
	s_waitcnt lgkmcnt(10)
	v_mfma_f32_16x16x32_bf16 v[4:7], v[16:19], v[12:15], v[4:7]
	s_waitcnt lgkmcnt(9)
	v_mfma_f32_16x16x32_bf16 v[8:11], v[20:23], v[12:15], v[8:11]
	s_waitcnt lgkmcnt(7)
	v_mfma_f32_16x16x32_bf16 v[4:7], v[28:31], v[24:27], v[4:7]
	s_waitcnt lgkmcnt(6)
	v_mfma_f32_16x16x32_bf16 v[8:11], v[32:35], v[24:27], v[8:11]
	s_waitcnt lgkmcnt(4)
	v_mfma_f32_16x16x32_bf16 v[4:7], v[40:43], v[36:39], v[4:7]
	s_waitcnt lgkmcnt(3)
	v_mfma_f32_16x16x32_bf16 v[8:11], v[44:47], v[36:39], v[8:11]
	s_waitcnt lgkmcnt(1)
	v_mfma_f32_16x16x32_bf16 v[4:7], v[52:55], v[48:51], v[4:7]
	s_waitcnt lgkmcnt(0)
	v_mfma_f32_16x16x32_bf16 v[8:11], v[56:59], v[48:51], v[8:11]
	v_lshlrev_b32_e32 v12, 3, v74
	v_mov_b32_e32 v13, v3
	v_lshl_add_u64 v[14:15], v[68:69], 0, v[12:13]
	s_mov_b32 s1, s19
	v_lshl_add_u64 v[14:15], v[14:15], 0, s[0:1]
	v_sub_co_u32_e32 v12, vcc, v14, v12
	v_cvt_pk_bf16_f32 v4, v4, v5
	s_nop 0
	v_subbrev_co_u32_e32 v13, vcc, 0, v15, vcc
	v_cvt_pk_bf16_f32 v5, v6, v7
	v_cvt_pk_bf16_f32 v6, v8, v9
	v_cvt_pk_bf16_f32 v7, v10, v11
	v_lshl_add_u64 v[8:9], v[12:13], 0, v[2:3]
	s_add_i32 s31, s31, s88
	s_add_i32 s30, s30, s90
	v_permlane16_swap_b32_e32 v4, v6
	v_permlane16_swap_b32_e32 v5, v7
	v_lshl_add_u64 v[0:1], v[8:9], 0, v[0:1]
	s_cmpk_gt_i32 s31, 0xff
	global_store_dwordx4 v[0:1], v[4:7], off
	s_barrier
	s_cbranch_scc0 .LBB0_349
	s_cmpk_lg_u32 s88, 0x100
	s_cbranch_scc1 .LBB0_350
	v_readlane_b32 s0, v255, 35
	s_bitcmp1_b32 s0, 3
	s_cbranch_scc1 .Lm1_after_scan

.Lm1_scan_entry:
	s_waitcnt lgkmcnt(0)
	s_barrier
	v_readlane_b32 s30, v251, 2
	v_readlane_b32 s31, v255, 35
	s_movk_i32 s78, 0xc00
	s_movk_i32 s91, 0x500
	s_movk_i32 s80, 0x600
	s_mov_b32 s81, 0x20000
	s_mov_b32 s92, 0x28000
	s_mov_b32 s93, 0x30000
	s_mov_b32 s96, 0x38000
	s_movk_i32 s97, 0x120
	s_mov_b32 s8, 0x40000
	s_movk_i32 s9, 0x700
	v_readlane_b32 s84, v255, 37
	v_readlane_b32 s85, v255, 38
	v_readlane_b32 s76, v255, 20
	v_readlane_b32 s77, v255, 21
	s_branch .LBB0_349
.Lm1_after_scan:
	v_readlane_b32 s96, v255, 14
	v_readlane_b32 s92, v255, 18
	v_readlane_b32 s84, v255, 22
	v_readlane_b32 s91, v255, 35
	v_readlane_b32 s97, v255, 15
	v_readlane_b32 s93, v255, 19
	v_readlane_b32 s85, v255, 23
	v_readlane_b32 s20, v252, 35
	v_readlane_b32 s21, v252, 36
	v_readlane_b32 s22, v252, 37
	v_readlane_b32 s23, v252, 38
	v_readlane_b32 s16, v252, 30
	s_movk_i32 s48, 0xc00
	s_branch .Lm1_att_end
.LBB0_499:
	s_cmpk_lg_u32 s88, 0x100
	s_cbranch_scc1 .Lm1_att_end
	v_readlane_b32 s0, v255, 35
	s_bitcmp1_b32 s0, 3
	s_cbranch_scc1 .Lm1_scan_entry
